# v31 + GLA head-norm 8-lane reductions via DPP quad_perm/row_half_mirror instead of ds_bpermute round trips
# speedup vs baseline: 1.0214x; 1.0031x over previous
; #define LAS __attribute__((address_space(3)))
; DI unsigned f2bf(float f) { unsigned u = __builtin_bit_cast(unsigned, f); return (u + 0x7fffu + ((u >> 16) & 1u)) >> 16; }
; DI f32x4 mma16(bf16x8 a, bf16x8 b, f32x4 c) { return __builtin_amdgcn_mfma_f32_16x16x32_bf16(a, b, c, 0, 0, 0); }
; DI v4u pack8(const float (&f)[8]) { v4u o; o.x = pk2(f[0], f[1]); o.y = pk2(f[2], f[3]); o.z = pk2(f[4], f[5]); o.w = pk2(f[6], f[7]); return o; }
; DI void gla_item(KA a, const int l, LAS unsigned char* lds, const int item) {
;     ...
;                 qo[e] = q8[e] * 0.125f * __expf(bv); ko[e] = k8[e] * __expf(-bv);
;                 KhT[k * PA + t] = (bf16)f2bf(k8[e] * __expf(tot - bv)); VT[k * PA + t] = (bf16)f2bf(v8[e]);
;                 if (t == 63) DEC[k] = __expf(tot); }
;             *(LAS v4u*)(Qt + t * PA + 8 * kg) = pack8(qo); *(LAS v4u*)(Kt + t * PA + 8 * kg) = pack8(ko);
;         }
;         __syncthreads();
;         f32x4 ao[2] = {ZERO4, ZERO4};
;         {
; #pragma unroll
;             for (int ks = 0; ks < 2; ++ks) { const bf16x8 aq = *(const LAS bf16x8*)(Qt + (16 * rt + fr) * PA + ks * 32 + fq * 8);
; #pragma unroll
;                 for (int i = 0; i < 2; ++i) { const bf16x8 bs = *(const LAS bf16x8*)(ST + (16 * (cp + i) + fr) * PA + ks * 32 + fq * 8); ao[i] = mma16(aq, bs, ao[i]); } }
;             f32x4 pp[2] = {ZERO4, ZERO4};
; #pragma unroll
;             for (int ks = 0; ks < 2; ++ks) { const bf16x8 aq = *(const LAS bf16x8*)(Qt + (16 * rt + fr) * PA + ks * 32 + fq * 8);
; #pragma unroll
;                 for (int i = 0; i < 2; ++i) { const bf16x8 bk = *(const LAS bf16x8*)(Kt + (16 * (cp + i) + fr) * PA + ks * 32 + fq * 8); pp[i] = mma16(aq, bk, pp[i]); } }
; #pragma unroll
;             for (int i = 0; i < 2; ++i)
; #pragma unroll
;                 for (int j = 0; j < 4; ++j) { const int tr = 16 * rt + 4 * fq + j, sc = 16 * (cp + i) + fr; Pm[tr * PA + sc] = (bf16)f2bf(sc <= tr ? pp[i][j] : 0.f); }
;         }
;         __syncthreads();
.LBB0_565:
	s_or_b64 exec, exec, s[0:1]
	v_mul_f32_e32 v43, 0x3fb8aa3b, v54
	v_mul_f32_e32 v54, 0xbfb8aa3b, v54
	v_exp_f32_e32 v54, v54
	v_lshlrev_b32_e32 v55, 16, v39
	v_and_b32_e32 v39, 0xffff0000, v39
	v_exp_f32_e32 v43, v43
	v_mul_f32_e32 v42, v54, v42
	v_mul_f32_e32 v54, 0x3fb8aa3b, v56
	v_exp_f32_e32 v54, v54
	v_mul_f32_e32 v39, 0x3e000000, v39
	v_mul_f32_e32 v55, 0x3e000000, v55
	v_mul_f32_e32 v43, v55, v43
	v_mul_f32_e32 v39, v39, v54
	v_mul_f32_e32 v54, 0x3fb8aa3b, v52
	v_mul_f32_e32 v52, 0xbfb8aa3b, v52
	v_exp_f32_e32 v52, v52
	v_mul_f32_e32 v55, 0xbfb8aa3b, v56
	v_exp_f32_e32 v55, v55
	v_exp_f32_e32 v54, v54
	v_mul_f32_e32 v41, v52, v41
	v_mul_f32_e32 v52, 0x3fb8aa3b, v53
	v_exp_f32_e32 v52, v52
	v_mul_f32_e32 v47, v55, v47
	v_lshlrev_b32_e32 v55, 16, v38
	v_and_b32_e32 v38, 0xffff0000, v38
	v_mul_f32_e32 v38, 0x3e000000, v38
	v_mul_f32_e32 v38, v38, v52
	v_mul_f32_e32 v52, 0x3fb8aa3b, v50
	v_mul_f32_e32 v50, 0xbfb8aa3b, v50
	v_exp_f32_e32 v50, v50
	v_mul_f32_e32 v53, 0xbfb8aa3b, v53
	v_exp_f32_e32 v53, v53
	v_exp_f32_e32 v52, v52
	v_mul_f32_e32 v40, v50, v40
	v_mul_f32_e32 v50, 0x3fb8aa3b, v51
	v_exp_f32_e32 v50, v50
	v_mul_f32_e32 v46, v53, v46
	v_lshlrev_b32_e32 v53, 16, v37
	v_mul_f32_e32 v51, 0xbfb8aa3b, v51
	v_and_b32_e32 v37, 0xffff0000, v37
	v_exp_f32_e32 v51, v51
	v_mul_f32_e32 v37, 0x3e000000, v37
	v_mul_f32_e32 v37, v37, v50
	v_mul_f32_e32 v50, 0x3fb8aa3b, v48
	v_exp_f32_e32 v50, v50
	v_mul_f32_e32 v45, v51, v45
	v_lshlrev_b32_e32 v51, 16, v36
	v_mul_f32_e32 v51, 0x3e000000, v51
	v_mul_f32_e32 v50, v51, v50
	v_mul_f32_e32 v51, 0x3fb8aa3b, v49
	v_mul_f32_e32 v48, 0xbfb8aa3b, v48
	v_exp_f32_e32 v51, v51
	v_mul_f32_e32 v49, 0xbfb8aa3b, v49
	v_exp_f32_e32 v48, v48
	v_exp_f32_e32 v49, v49
	v_and_b32_e32 v36, 0xffff0000, v36
	v_mul_f32_e32 v55, 0x3e000000, v55
	v_mul_f32_e32 v53, 0x3e000000, v53
	v_mul_f32_e32 v36, 0x3e000000, v36
	v_mul_f32_e32 v54, v55, v54
	v_mul_f32_e32 v52, v53, v52
	v_mul_f32_e32 v36, v36, v51
	v_mul_f32_e32 v48, v48, v170
	v_mul_f32_e32 v44, v49, v44
	v_cvt_pk_bf16_f32 v36, v50, v36
	v_cvt_pk_bf16_f32 v37, v52, v37
	v_cvt_pk_bf16_f32 v38, v54, v38
	v_cvt_pk_bf16_f32 v39, v43, v39
	ds_write_b128 v140, v[36:39] offset:40960
	v_cvt_pk_bf16_f32 v36, v48, v44
	v_cvt_pk_bf16_f32 v37, v40, v45
	v_cvt_pk_bf16_f32 v38, v41, v46
	v_cvt_pk_bf16_f32 v39, v42, v47
	ds_write_b128 v140, v[36:39] offset:50176
	s_waitcnt lgkmcnt(0)
	s_barrier
	ds_read_b128 v[36:39], v142 offset:40960
	ds_read_b128 v[48:51], v142 offset:41024
	v_add_u32_e32 v52, v143, v159
	ds_read_b128 v[40:43], v52
	v_add_u32_e32 v60, v143, v160
	ds_read_b128 v[44:47], v60
	ds_read_b128 v[52:55], v52 offset:64
	s_waitcnt lgkmcnt(2)
	v_mfma_f32_16x16x32_bf16 v[40:43], v[36:39], v[40:43], 0
	v_add_u32_e32 v61, v141, v159
	v_add_u32_e32 v62, v141, v160
	ds_read_b128 v[56:59], v62 offset:50176
	s_waitcnt lgkmcnt(1)
	v_mfma_f32_16x16x32_bf16 v[40:43], v[48:51], v[52:55], v[40:43]
	ds_read_b128 v[52:55], v61 offset:50176
	s_movk_i32 s0, 0x7fff
	v_add_u32_e32 v64, v145, v159
	v_mfma_f32_16x16x32_bf16 v[44:47], v[36:39], v[44:47], 0
	s_add_u32 s4, s4, 0x70000
	s_addc_u32 s5, s5, 0
	s_cmp_lg_u32 s4, 0xe00000
	s_waitcnt lgkmcnt(0)
	v_mfma_f32_16x16x32_bf16 v[52:55], v[36:39], v[52:55], 0
	v_mfma_f32_16x16x32_bf16 v[36:39], v[36:39], v[56:59], 0
	ds_read_b128 v[56:59], v61 offset:50240
	s_waitcnt lgkmcnt(0)
	v_mfma_f32_16x16x32_bf16 v[52:55], v[48:51], v[56:59], v[52:55]
	ds_read_b128 v[56:59], v62 offset:50240
	ds_read_b128 v[60:63], v60 offset:64
	s_waitcnt lgkmcnt(1)
	v_mfma_f32_16x16x32_bf16 v[36:39], v[48:51], v[56:59], v[36:39]
	s_nop 3
	v_cndmask_b32_e64 v52, v52, 0, s[58:59]
	v_bfe_u32 v56, v52, 16, 1
	v_add3_u32 v52, v52, v56, s0
	ds_write_b16_d16_hi v167, v52
	v_cndmask_b32_e64 v52, v53, 0, s[60:61]
	v_bfe_u32 v53, v52, 16, 1
	v_add3_u32 v52, v52, v53, s0
	ds_write_b16_d16_hi v167, v52 offset:144
	v_cndmask_b32_e64 v52, v54, 0, s[62:63]
	v_bfe_u32 v53, v52, 16, 1
	v_add3_u32 v52, v52, v53, s0
	ds_write_b16_d16_hi v167, v52 offset:288
	v_cndmask_b32_e64 v52, v55, 0, s[64:65]
	v_bfe_u32 v53, v52, 16, 1
	v_add3_u32 v52, v52, v53, s0
	v_cndmask_b32_e64 v36, v36, 0, s[66:67]
	ds_write_b16_d16_hi v167, v52 offset:432
	v_bfe_u32 v52, v36, 16, 1
	v_add3_u32 v36, v36, v52, s0
	ds_write_b16_d16_hi v168, v36
	v_cndmask_b32_e64 v36, v37, 0, s[68:69]
	v_bfe_u32 v37, v36, 16, 1
	v_add3_u32 v36, v36, v37, s0
	ds_write_b16_d16_hi v168, v36 offset:144
	v_cndmask_b32_e64 v36, v38, 0, s[70:71]
	v_bfe_u32 v37, v36, 16, 1
	v_add3_u32 v36, v36, v37, s0
	ds_write_b16_d16_hi v168, v36 offset:288
	v_cndmask_b32_e64 v36, v39, 0, s[2:3]
	v_bfe_u32 v37, v36, 16, 1
	v_add3_u32 v36, v36, v37, s0
	ds_write_b16_d16_hi v168, v36 offset:432
	s_waitcnt lgkmcnt(0)
	s_barrier
; #define LAS __attribute__((address_space(3)))
; DI f32x4 mma16(bf16x8 a, bf16x8 b, f32x4 c) { return __builtin_amdgcn_mfma_f32_16x16x32_bf16(a, b, c, 0, 0, 0); }
; DI void gla_item(KA a, const int l, LAS unsigned char* lds, const int item) {
;     ...
;         {
; #pragma unroll
;             for (int ks = 0; ks < 2; ++ks) { const bf16x8 ap = *(const LAS bf16x8*)(Pm + (16 * rt + fr) * PA + ks * 32 + fq * 8); const bf16x8 ak = *(const LAS bf16x8*)(KhT + (16 * rt + fr) * PA + ks * 32 + fq * 8);
;                 f32x4 u[2];
; #pragma unroll
;                 for (int i = 0; i < 2; ++i) { const bf16x8 bv = *(const LAS bf16x8*)(VT + (16 * (cp + i) + fr) * PA + ks * 32 + fq * 8); ao[i] = mma16(ap, bv, ao[i]);
;                     if (ks == 0) { f32x4 sd; for (int j = 0; j < 4; ++j) sd[j] = S[i][j] * DEC[16 * rt + 4 * fq + j]; S[i] = sd; }
;                     S[i] = mma16(ak, bv, S[i]); }
;             }
; #pragma unroll
;             for (int i = 0; i < 2; ++i)
; #pragma unroll
;                 for (int j = 0; j < 4; ++j) OUTF[(16 * rt + 4 * fq + j) * 64 + 16 * (cp + i) + fr] = ao[i][j];
;         }
;         __syncthreads();
	ds_read_b128 v[36:39], v144
	v_mfma_f32_16x16x32_bf16 v[44:47], v[48:51], v[60:63], v[44:47]
	ds_read_b128 v[48:51], v64
	v_add_u32_e32 v60, v145, v160
	ds_read_b128 v[52:55], v60
	ds_read_b128 v[56:59], v142 offset:59392
	s_waitcnt lgkmcnt(2)
	v_mfma_f32_16x16x32_bf16 v[40:43], v[36:39], v[48:51], v[40:43]
	v_and_b32_e32 v61, 0xffff0000, v3
	v_and_b32_e32 v63, 0xffff0000, v2
	s_mov_b32 s0, 0xf800000
	s_waitcnt lgkmcnt(1)
	v_mfma_f32_16x16x32_bf16 v[36:39], v[36:39], v[52:55], v[44:47]
	v_lshlrev_b32_e32 v62, 16, v2
	v_mul_f32_e32 v2, 0xbfb8aa3b, v62
	v_exp_f32_e32 v2, v2
	ds_read_b128 v[44:47], v169 offset:39168
	v_add_f32_e32 v2, 1.0, v2
	v_rcp_f32_e32 v2, v2
	s_waitcnt lgkmcnt(0)
	v_pk_mul_f32 v[32:33], v[32:33], v[44:45]
	v_pk_mul_f32 v[34:35], v[34:35], v[46:47]
	v_pk_mul_f32 v[28:29], v[28:29], v[44:45]
	v_pk_mul_f32 v[30:31], v[30:31], v[46:47]
	v_mfma_f32_16x16x32_bf16 v[32:35], v[56:59], v[48:51], v[32:35]
	ds_read_b128 v[48:51], v144 offset:64
	ds_read_b128 v[44:47], v64 offset:64
	v_mfma_f32_16x16x32_bf16 v[28:31], v[56:59], v[52:55], v[28:31]
	ds_read_b128 v[52:55], v142 offset:59456
	s_waitcnt lgkmcnt(1)
	v_mfma_f32_16x16x32_bf16 v[40:43], v[48:51], v[44:47], v[40:43]
	s_waitcnt lgkmcnt(0)
	v_mfma_f32_16x16x32_bf16 v[32:35], v[52:55], v[44:47], v[32:35]
	ds_read_b128 v[44:47], v60 offset:64
	v_lshlrev_b32_e32 v60, 16, v3
	s_waitcnt lgkmcnt(0)
	v_mfma_f32_16x16x32_bf16 v[36:39], v[48:51], v[44:47], v[36:39]
	v_mfma_f32_16x16x32_bf16 v[28:31], v[52:55], v[44:47], v[28:31]
	v_add_u32_e32 v44, v162, v161
	ds_write_b32 v44, v40 offset:16384
	v_add_u32_e32 v40, v162, v163
	ds_write_b32 v40, v41 offset:16384
	v_add_u32_e32 v40, v162, v164
	ds_write_b32 v40, v42 offset:16384
	v_add_u32_e32 v40, v162, v165
	ds_write_b32 v40, v43 offset:16384
	v_add_u32_e32 v40, v166, v161
	ds_write_b32 v40, v36 offset:16384
	v_add_u32_e32 v36, v166, v163
	ds_write_b32 v36, v37 offset:16384
	v_add_u32_e32 v36, v166, v164
	ds_write_b32 v36, v38 offset:16384
	v_add_u32_e32 v36, v166, v165
	ds_write_b32 v36, v39 offset:16384
	v_cvt_pk_bf16_f32 v36, v32, v33
	v_cvt_pk_bf16_f32 v37, v34, v35
	v_add_u32_e32 v38, v146, v159
	s_waitcnt lgkmcnt(0)
	s_barrier
; #define LAS __attribute__((address_space(3)))
; DI unsigned pk2(float lo, float hi) { const f32x2 v = {lo, hi}; const bf16x2_t b = __builtin_convertvector(v, bf16x2_t); return __builtin_bit_cast(unsigned, b); }
; DI float sigmoidf_(float x) { return __builtin_amdgcn_rcpf(1.f + __expf(-x)); }
; DI void unpack8(const v4u u, float (&f)[8]) { f[0] = bflo(u.x); f[1] = bfhi(u.x); f[2] = bflo(u.y); f[3] = bfhi(u.y); f[4] = bflo(u.z); f[5] = bfhi(u.z); f[6] = bflo(u.w); f[7] = bfhi(u.w); }
; DI v4u pack8(const float (&f)[8]) { v4u o; o.x = pk2(f[0], f[1]); o.y = pk2(f[2], f[3]); o.z = pk2(f[4], f[5]); o.w = pk2(f[6], f[7]); return o; }
; DI void gla_item(KA a, const int l, LAS unsigned char* lds, const int item) {
;     ...
;         {
; #pragma unroll
;             for (int i = 0; i < 2; ++i) { v2u p; p.x = pk2(S[i][0], S[i][1]); p.y = pk2(S[i][2], S[i][3]); *(LAS v2u*)(ST + (16 * (cp + i) + fr) * PA + 16 * rt + 4 * fq) = p; }
;             float x[8], sm = 0.f;
; #pragma unroll
;             for (int e = 0; e < 8; ++e) { x[e] = OUTF[t * 64 + 8 * kg + e]; sm += x[e]; }
;             sm += __shfl_xor(sm, 1); sm += __shfl_xor(sm, 2); sm += __shfl_xor(sm, 4);
;             const float mean = sm * (1.f / 64.f); float qv = 0.f;
; #pragma unroll
;             for (int e = 0; e < 8; ++e) { x[e] -= mean; qv += x[e] * x[e]; }
;             qv += __shfl_xor(qv, 1); qv += __shfl_xor(qv, 2); qv += __shfl_xor(qv, 4);
;             const float rstd = 1.f / sqrtf(qv * (1.f / 64.f) + LN_EPS);
;             float g8[8], o[8]; unpack8(cg_, g8);
; #pragma unroll
;             for (int e = 0; e < 8; ++e) { const float yv = x[e] * rstd * lnw[8 * kg + e] + lnb[8 * kg + e]; o[e] = yv * g8[e] * sigmoidf_(g8[e]); }
;             *(v4u*)(act + (tb + t) * D + hh * 64 + 8 * kg) = pack8(o);
	ds_write_b64 v38, v[36:37]
	v_cvt_pk_bf16_f32 v36, v28, v29
	v_cvt_pk_bf16_f32 v37, v30, v31
	v_add_u32_e32 v38, v146, v160
	ds_write_b64 v38, v[36:37]
	ds_read_b128 v[36:39], v138 offset:16384
	ds_read_b128 v[40:43], v138 offset:16400
	global_load_dwordx4 v[44:47], v[116:117], off offset:16
	global_load_dwordx4 v[48:51], v[116:117], off
	s_waitcnt lgkmcnt(1)
	v_add_f32_e32 v3, 0, v36
	v_add_f32_e32 v3, v3, v37
	v_add_f32_e32 v3, v3, v38
	v_add_f32_e32 v3, v3, v39
	s_waitcnt lgkmcnt(0)
	v_add_f32_e32 v3, v3, v40
	v_add_f32_e32 v3, v3, v41
	v_add_f32_e32 v3, v3, v42
	v_add_f32_e32 v3, v3, v43
	s_nop 1
	s_waitcnt lgkmcnt(0)
	v_add_f32_dpp v3, v3, v3 quad_perm:[1,0,3,2] row_mask:0xf bank_mask:0xf
	v_mul_f32_e32 v52, 0xbfb8aa3b, v63
	v_exp_f32_e32 v65, v52
	global_load_dwordx4 v[52:55], v[118:119], off offset:16
	global_load_dwordx4 v[56:59], v[118:119], off
	s_nop 1
	s_waitcnt lgkmcnt(0)
	v_add_f32_dpp v66, v3, v3 quad_perm:[2,3,0,1] row_mask:0xf bank_mask:0xf
	s_nop 1
	v_add_f32_e32 v3, 1.0, v65
	v_lshlrev_b32_e32 v64, 16, v1
	v_and_b32_e32 v65, 0xffff0000, v1
	v_rcp_f32_e32 v3, v3
	s_waitcnt lgkmcnt(0)
	v_add_f32_dpp v1, v66, v66 row_half_mirror row_mask:0xf bank_mask:0xf
	v_mul_f32_e32 v66, 0x3c800000, v1
	v_pk_add_f32 v[36:37], v[36:37], v[66:67] op_sel_hi:[1,0] neg_lo:[0,1] neg_hi:[0,1]
	v_pk_add_f32 v[38:39], v[38:39], v[66:67] op_sel_hi:[1,0] neg_lo:[0,1] neg_hi:[0,1]
	v_pk_mul_f32 v[68:69], v[36:37], v[36:37]
	v_pk_mul_f32 v[70:71], v[38:39], v[38:39]
	v_add_f32_e32 v1, v68, v69
	v_pk_add_f32 v[40:41], v[40:41], v[66:67] op_sel_hi:[1,0] neg_lo:[0,1] neg_hi:[0,1]
	v_add_f32_e32 v1, v70, v1
	v_pk_mul_f32 v[72:73], v[40:41], v[40:41]
	v_add_f32_e32 v1, v71, v1
	v_pk_add_f32 v[42:43], v[42:43], v[66:67] op_sel_hi:[1,0] neg_lo:[0,1] neg_hi:[0,1]
	v_add_f32_e32 v1, v72, v1
	v_pk_mul_f32 v[66:67], v[42:43], v[42:43]
	v_add_f32_e32 v1, v73, v1
	v_add_f32_e32 v1, v66, v1
	v_add_f32_e32 v1, v67, v1
	s_nop 1
	v_mul_f32_e32 v67, 0xbfb8aa3b, v64
	v_mul_f32_e32 v68, 0xbfb8aa3b, v65
	v_exp_f32_e32 v67, v67
	v_exp_f32_e32 v68, v68
	s_waitcnt lgkmcnt(0)
	v_add_f32_dpp v1, v1, v1 quad_perm:[1,0,3,2] row_mask:0xf bank_mask:0xf
	s_nop 1
	v_add_f32_e32 v66, 1.0, v67
	v_add_f32_e32 v67, 1.0, v68
	v_lshlrev_b32_e32 v68, 16, v0
	v_rcp_f32_e32 v66, v66
	s_waitcnt lgkmcnt(0)
	v_add_f32_dpp v1, v1, v1 quad_perm:[2,3,0,1] row_mask:0xf bank_mask:0xf
	s_nop 1
	v_and_b32_e32 v69, 0xffff0000, v0
	v_mul_f32_e32 v71, 0xbfb8aa3b, v69
	v_exp_f32_e32 v71, v71
	v_mul_f32_e32 v0, 0xbfb8aa3b, v68
	s_waitcnt lgkmcnt(0)
	v_add_f32_dpp v1, v1, v1 row_half_mirror row_mask:0xf bank_mask:0xf
	v_fmamk_f32 v1, v1, 0x3c800000, v235
	v_mul_f32_e32 v70, 0x4f800000, v1
	v_cmp_gt_f32_e32 vcc, s0, v1
	v_exp_f32_e32 v0, v0
	v_rcp_f32_e32 v67, v67
	v_cndmask_b32_e32 v1, v1, v70, vcc
	v_sqrt_f32_e32 v70, v1
	v_add_f32_e32 v0, 1.0, v0
	v_rcp_f32_e32 v0, v0
	v_add_u32_e32 v72, -1, v70
	v_fma_f32 v73, -v72, v70, v1
	v_cmp_ge_f32_e64 s[0:1], 0, v73
	v_add_u32_e32 v73, 1, v70
	s_nop 0
	v_cndmask_b32_e64 v72, v70, v72, s[0:1]
	v_fma_f32 v70, -v73, v70, v1
	v_cmp_lt_f32_e64 s[0:1], 0, v70
	s_nop 1
	v_cndmask_b32_e64 v70, v72, v73, s[0:1]
	v_mul_f32_e32 v72, 0x37800000, v70
	v_cndmask_b32_e32 v70, v70, v72, vcc
	v_cmp_class_f32_e32 vcc, v1, v234
	s_nop 1
	v_cndmask_b32_e32 v70, v70, v1, vcc
	v_div_scale_f32 v72, s[0:1], v70, v70, 1.0
	v_rcp_f32_e32 v73, v72
	v_add_f32_e32 v1, 1.0, v71
	v_rcp_f32_e32 v1, v1
	s_mov_b64 s[0:1], 0x20000
	v_fma_f32 v71, -v72, v73, 1.0
	v_fmac_f32_e32 v73, v71, v73
	v_div_scale_f32 v71, vcc, 1.0, v70, 1.0
	v_mul_f32_e32 v74, v71, v73
	v_fma_f32 v75, -v72, v74, v71
	v_fmac_f32_e32 v74, v75, v73
	v_fma_f32 v71, -v72, v74, v71
	v_div_fmas_f32 v71, v71, v73, v74
	v_div_fixup_f32 v70, v71, v70, 1.0
	v_pk_mul_f32 v[36:37], v[36:37], v[70:71] op_sel_hi:[1,0]
	s_waitcnt vmcnt(0)
	v_pk_fma_f32 v[36:37], v[48:49], v[36:37], v[56:57]
	s_nop 0
	v_pk_mul_f32 v[36:37], v[36:37], v[68:69]
	s_nop 0
	v_pk_mul_f32 v[0:1], v[0:1], v[36:37]
	v_pk_mul_f32 v[36:37], v[38:39], v[70:71] op_sel_hi:[1,0]
	v_pk_mul_f32 v[38:39], v[40:41], v[70:71] op_sel_hi:[1,0]
	v_mul_f32_e32 v40, 0xbfb8aa3b, v60
	v_mul_f32_e32 v41, 0xbfb8aa3b, v61
	v_exp_f32_e32 v40, v40
	v_exp_f32_e32 v41, v41
	v_pk_fma_f32 v[38:39], v[44:45], v[38:39], v[52:53]
	v_pk_fma_f32 v[36:37], v[50:51], v[36:37], v[58:59]
	v_pk_mul_f32 v[38:39], v[38:39], v[62:63]
	v_pk_mul_f32 v[36:37], v[36:37], v[64:65]
	v_pk_mul_f32 v[2:3], v[2:3], v[38:39]
	v_add_f32_e32 v38, 1.0, v40
	v_add_f32_e32 v39, 1.0, v41
	v_rcp_f32_e32 v38, v38
	v_rcp_f32_e32 v39, v39
	v_pk_mul_f32 v[40:41], v[42:43], v[70:71] op_sel_hi:[1,0]
	v_pk_mul_f32 v[36:37], v[66:67], v[36:37]
	v_pk_fma_f32 v[40:41], v[46:47], v[40:41], v[54:55]
	v_cvt_pk_bf16_f32 v0, v0, v1
	v_pk_mul_f32 v[40:41], v[40:41], v[60:61]
	v_cvt_pk_bf16_f32 v1, v36, v37
	v_pk_mul_f32 v[38:39], v[38:39], v[40:41]
	v_cvt_pk_bf16_f32 v2, v2, v3
	v_cvt_pk_bf16_f32 v3, v38, v39
	global_store_dwordx4 v[120:121], v[0:3], off
	v_mov_b64_e32 v[38:39], v[18:19]
	v_mov_b64_e32 v[46:47], v[14:15]
	v_mov_b64_e32 v[42:43], v[10:11]
	v_mov_b64_e32 v[0:1], v[4:5]
	v_mov_b64_e32 v[54:55], v[26:27]
	v_mov_b64_e32 v[50:51], v[22:23]
	v_lshl_add_u64 v[120:121], v[120:121], 0, s[0:1]
	v_mov_b64_e32 v[36:37], v[16:17]
	v_mov_b64_e32 v[44:45], v[12:13]
	v_mov_b64_e32 v[40:41], v[8:9]
	v_mov_b64_e32 v[2:3], v[6:7]
	v_mov_b64_e32 v[52:53], v[24:25]
	v_mov_b64_e32 v[48:49], v[20:21]
	s_cbranch_scc0 .LBB0_584
